# prologue: context copy (4 loads in flight) and silu(c) staging (18 loads in flight) de-serialised
# baseline (speedup 1.0000x reference)
; __device__ __forceinline__ void prologue(const __attribute__((address_space(4))) Args& a, ldsp lds, int gw, int NGW, int wave, int lane, const int tid, const int bid, const int G) {
;     ...
;     { const f32x4* src = (const f32x4*)a.ctx; f32x4* dst = (f32x4*)(ws + WS_XC); for (int i = gw * 64 + lane; i < MC * D / 4; i += NGW * 64) dst[i] = src[i]; }
.LBB0_1266:
	v_lshl_or_b32 v0, s86, 6, v4
	s_mov_b32 s0, 0x80000
	v_cmp_gt_i32_e32 vcc, s0, v0
	s_waitcnt lgkmcnt(0)
	s_and_saveexec_b64 s[4:5], vcc
	v_readlane_b32 s12, v254, 17
	v_readlane_b32 s10, v254, 15
	v_readlane_b32 s13, v254, 18
	v_readlane_b32 s11, v254, 16
	s_cbranch_execz .LBB0_1269
	s_load_dwordx2 s[6:7], s[62:63], 0x10
	v_lshlrev_b32_e32 v2, 4, v0
	s_mov_b64 s[22:23], s[66:67]
	s_waitcnt lgkmcnt(0)
	global_load_dwordx4 v[98:101], v2, s[6:7]
	s_add_u32 s6, s6, 0x200000
	s_addc_u32 s7, s7, 0
	global_load_dwordx4 v[102:105], v2, s[6:7]
	s_add_u32 s6, s6, 0x200000
	s_addc_u32 s7, s7, 0
	global_load_dwordx4 v[106:109], v2, s[6:7]
	s_add_u32 s6, s6, 0x200000
	s_addc_u32 s7, s7, 0
	global_load_dwordx4 v[110:113], v2, s[6:7]
	s_waitcnt vmcnt(0)
	global_store_dwordx4 v2, v[98:101], s[22:23]
	s_add_u32 s22, s22, 0x200000
	s_addc_u32 s23, s23, 0
	global_store_dwordx4 v2, v[102:105], s[22:23]
	s_add_u32 s22, s22, 0x200000
	s_addc_u32 s23, s23, 0
	global_store_dwordx4 v2, v[106:109], s[22:23]
	s_add_u32 s22, s22, 0x200000
	s_addc_u32 s23, s23, 0
	global_store_dwordx4 v2, v[110:113], s[22:23]

; #define LAS __attribute__((address_space(3)))
; __device__ __forceinline__ float silu_f(float x) { return x * __builtin_amdgcn_rcpf(1.0f + __builtin_amdgcn_exp2f(x * -1.4426950408889634f)); }
; __device__ __forceinline__ void prologue(const __attribute__((address_space(4))) Args& a, ldsp lds, int gw, int NGW, int wave, int lane, const int tid, const int bid, const int G) {
;     ...
;     __syncthreads();
;     LAS float* sc = (LAS float*)(lds + 69632);
;     LAS float* red = (LAS float*)(lds + 106496);
;     for (int i = tid; i < 9 * D; i += 512) { const float v = (i < 8 * D) ? a.c[i] : a.c_ctx[i - 8 * D]; sc[i] = silu_f(v); }
;     __syncthreads();
.LBB0_1271:
	s_or_b64 exec, exec, s[4:5]
	s_movk_i32 s0, 0x2400
	v_cmp_gt_i32_e32 vcc, s0, v196
	s_waitcnt vmcnt(0) lgkmcnt(0)
	s_barrier
	s_and_saveexec_b64 s[4:5], vcc
	s_cbranch_execz .LBB0_1274
	s_load_dwordx2 s[0:1], s[62:63], 0x8
	s_load_dwordx2 s[6:7], s[62:63], 0x18
	v_readlane_b32 s3, v254, 21
	v_lshlrev_b32_e32 v0, 2, v196
	s_waitcnt lgkmcnt(0)
	global_load_dword v98, v0, s[0:1]
	global_load_dword v99, v0, s[0:1] offset:2048
	s_add_u32 s0, s0, 0x1000
	s_addc_u32 s1, s1, 0
	global_load_dword v100, v0, s[0:1]
	global_load_dword v101, v0, s[0:1] offset:2048
	s_add_u32 s0, s0, 0x1000
	s_addc_u32 s1, s1, 0
	global_load_dword v102, v0, s[0:1]
	global_load_dword v103, v0, s[0:1] offset:2048
	s_add_u32 s0, s0, 0x1000
	s_addc_u32 s1, s1, 0
	global_load_dword v104, v0, s[0:1]
	global_load_dword v105, v0, s[0:1] offset:2048
	s_add_u32 s0, s0, 0x1000
	s_addc_u32 s1, s1, 0
	global_load_dword v106, v0, s[0:1]
	global_load_dword v107, v0, s[0:1] offset:2048
	s_add_u32 s0, s0, 0x1000
	s_addc_u32 s1, s1, 0
	global_load_dword v108, v0, s[0:1]
	global_load_dword v109, v0, s[0:1] offset:2048
	s_add_u32 s0, s0, 0x1000
	s_addc_u32 s1, s1, 0
	global_load_dword v110, v0, s[0:1]
	global_load_dword v111, v0, s[0:1] offset:2048
	s_add_u32 s0, s0, 0x1000
	s_addc_u32 s1, s1, 0
	global_load_dword v112, v0, s[0:1]
	global_load_dword v113, v0, s[0:1] offset:2048
	global_load_dword v114, v0, s[6:7]
	global_load_dword v115, v0, s[6:7] offset:2048
	v_add_u32_e32 v2, s3, v0
	s_waitcnt vmcnt(0)
	v_mul_f32_e32 v116, 0xbfb8aa3b, v98
	v_mul_f32_e32 v117, 0xbfb8aa3b, v99
	v_mul_f32_e32 v118, 0xbfb8aa3b, v100
	v_mul_f32_e32 v119, 0xbfb8aa3b, v101
	v_mul_f32_e32 v120, 0xbfb8aa3b, v102
	v_mul_f32_e32 v121, 0xbfb8aa3b, v103
	v_mul_f32_e32 v122, 0xbfb8aa3b, v104
	v_mul_f32_e32 v123, 0xbfb8aa3b, v105
	v_mul_f32_e32 v124, 0xbfb8aa3b, v106
	v_mul_f32_e32 v125, 0xbfb8aa3b, v107
	v_mul_f32_e32 v126, 0xbfb8aa3b, v108
	v_mul_f32_e32 v127, 0xbfb8aa3b, v109
	v_mul_f32_e32 v128, 0xbfb8aa3b, v110
	v_mul_f32_e32 v129, 0xbfb8aa3b, v111
	v_mul_f32_e32 v130, 0xbfb8aa3b, v112
	v_mul_f32_e32 v131, 0xbfb8aa3b, v113
	v_mul_f32_e32 v132, 0xbfb8aa3b, v114
	v_mul_f32_e32 v133, 0xbfb8aa3b, v115
	v_exp_f32_e32 v116, v116
	v_exp_f32_e32 v117, v117
	v_exp_f32_e32 v118, v118
	v_exp_f32_e32 v119, v119
	v_exp_f32_e32 v120, v120
	v_exp_f32_e32 v121, v121
	v_exp_f32_e32 v122, v122
	v_exp_f32_e32 v123, v123
	v_exp_f32_e32 v124, v124
	v_exp_f32_e32 v125, v125
	v_exp_f32_e32 v126, v126
	v_exp_f32_e32 v127, v127
	v_exp_f32_e32 v128, v128
	v_exp_f32_e32 v129, v129
	v_exp_f32_e32 v130, v130
	v_exp_f32_e32 v131, v131
	v_exp_f32_e32 v132, v132
	v_exp_f32_e32 v133, v133
	v_add_f32_e32 v116, 1.0, v116
	v_add_f32_e32 v117, 1.0, v117
	v_add_f32_e32 v118, 1.0, v118
	v_add_f32_e32 v119, 1.0, v119
	v_add_f32_e32 v120, 1.0, v120
	v_add_f32_e32 v121, 1.0, v121
	v_add_f32_e32 v122, 1.0, v122
	v_add_f32_e32 v123, 1.0, v123
	v_add_f32_e32 v124, 1.0, v124
	v_add_f32_e32 v125, 1.0, v125
	v_add_f32_e32 v126, 1.0, v126
	v_add_f32_e32 v127, 1.0, v127
	v_add_f32_e32 v128, 1.0, v128
	v_add_f32_e32 v129, 1.0, v129
	v_add_f32_e32 v130, 1.0, v130
	v_add_f32_e32 v131, 1.0, v131
	v_add_f32_e32 v132, 1.0, v132
	v_add_f32_e32 v133, 1.0, v133
	v_rcp_f32_e32 v116, v116
	v_rcp_f32_e32 v117, v117
	v_rcp_f32_e32 v118, v118
	v_rcp_f32_e32 v119, v119
	v_rcp_f32_e32 v120, v120
	v_rcp_f32_e32 v121, v121
	v_rcp_f32_e32 v122, v122
	v_rcp_f32_e32 v123, v123
	v_rcp_f32_e32 v124, v124
	v_rcp_f32_e32 v125, v125
	v_rcp_f32_e32 v126, v126
	v_rcp_f32_e32 v127, v127
	v_rcp_f32_e32 v128, v128
	v_rcp_f32_e32 v129, v129
	v_rcp_f32_e32 v130, v130
	v_rcp_f32_e32 v131, v131
	v_rcp_f32_e32 v132, v132
	v_rcp_f32_e32 v133, v133
	v_mul_f32_e32 v98, v98, v116
	v_mul_f32_e32 v99, v99, v117
	v_mul_f32_e32 v100, v100, v118
	v_mul_f32_e32 v101, v101, v119
	v_mul_f32_e32 v102, v102, v120
	v_mul_f32_e32 v103, v103, v121
	v_mul_f32_e32 v104, v104, v122
	v_mul_f32_e32 v105, v105, v123
	v_mul_f32_e32 v106, v106, v124
	v_mul_f32_e32 v107, v107, v125
	v_mul_f32_e32 v108, v108, v126
	v_mul_f32_e32 v109, v109, v127
	v_mul_f32_e32 v110, v110, v128
	v_mul_f32_e32 v111, v111, v129
	v_mul_f32_e32 v112, v112, v130
	v_mul_f32_e32 v113, v113, v131
	v_mul_f32_e32 v114, v114, v132
	v_mul_f32_e32 v115, v115, v133
	ds_write_b32 v2, v98
	ds_write_b32 v2, v99 offset:2048
	ds_write_b32 v2, v100 offset:4096
	ds_write_b32 v2, v101 offset:6144
	ds_write_b32 v2, v102 offset:8192
	ds_write_b32 v2, v103 offset:10240
	ds_write_b32 v2, v104 offset:12288
	ds_write_b32 v2, v105 offset:14336
	ds_write_b32 v2, v106 offset:16384
	ds_write_b32 v2, v107 offset:18432
	ds_write_b32 v2, v108 offset:20480
	ds_write_b32 v2, v109 offset:22528
	ds_write_b32 v2, v110 offset:24576
	ds_write_b32 v2, v111 offset:26624
	ds_write_b32 v2, v112 offset:28672
	ds_write_b32 v2, v113 offset:30720
	ds_write_b32 v2, v114 offset:32768
	ds_write_b32 v2, v115 offset:34816
